# L2 residency / streaming writes: the prep phase's full-line xb (bf16 activations) stores marked non-temporal (timing-only)
# speedup vs baseline: 1.0084x; 1.0084x over previous
.LBB0_31:
	s_movk_i32 s4, 0xc7f0
	s_mov_b32 s5, -1
	s_waitcnt lgkmcnt(0)
	v_add_co_u32_e32 v2, vcc, 0xffffd000, v52
	v_lshl_add_u64 v[4:5], v[52:53], 0, s[4:5]
	s_movk_i32 s4, 0xcff0
	v_addc_co_u32_e32 v3, vcc, -1, v53, vcc
	s_mov_b32 s5, -1
	global_load_dwordx4 v[56:59], v[2:3], off offset:-2064
	global_load_dwordx4 v[68:71], v[4:5], off offset:16
	global_load_dwordx4 v[72:75], v[2:3], off offset:-16
	v_lshl_add_u64 v[2:3], v[52:53], 0, s[4:5]
	global_load_dwordx4 v[76:79], v[2:3], off offset:16
	s_movk_i32 s4, 0xd7f0
	s_mov_b32 s5, -1
	v_lshl_add_u64 v[18:19], v[52:53], 0, s[4:5]
	s_movk_i32 s4, 0xdff0
	s_mov_b32 s5, -1
	v_add_co_u32_e32 v24, vcc, 0xffffe000, v52
	v_lshl_add_u64 v[20:21], v[52:53], 0, s[4:5]
	s_movk_i32 s4, 0xe7f0
	v_addc_co_u32_e32 v25, vcc, -1, v53, vcc
	s_mov_b32 s5, -1
	v_add_co_u32_e32 v30, vcc, 0xfffff000, v52
	v_lshl_add_u64 v[22:23], v[52:53], 0, s[4:5]
	s_nop 0
	v_addc_co_u32_e32 v31, vcc, -1, v53, vcc
	global_load_dwordx4 v[10:13], v[52:53], off offset:-2048
	global_load_dwordx4 v[14:17], v[52:53], off offset:-2064
	global_load_dwordx4 v[2:5], v[52:53], off
	global_load_dwordx4 v[6:9], v[52:53], off offset:-16
	global_load_dwordx4 v[46:49], v[24:25], off offset:-2064
	global_load_dwordx4 v[42:45], v[18:19], off offset:16
	global_load_dwordx4 v[38:41], v[24:25], off offset:-16
	global_load_dwordx4 v[34:37], v[20:21], off offset:16
	global_load_dwordx4 v[26:29], v[30:31], off offset:-2064
	s_nop 0
	global_load_dwordx4 v[22:25], v[22:23], off offset:16
	s_nop 0
	global_load_dwordx4 v[18:21], v[30:31], off offset:-16
	s_nop 0
	global_load_dwordx4 v[30:33], v[52:53], off offset:-4096
	s_mov_b32 s4, 0x3100000
	s_waitcnt vmcnt(15)
	v_cvt_pk_bf16_f32 v80, v56, v57
	v_cvt_pk_bf16_f32 v81, v58, v59
	s_waitcnt vmcnt(14)
	v_cvt_pk_bf16_f32 v82, v68, v69
	s_waitcnt vmcnt(13)
	v_cvt_pk_bf16_f32 v68, v72, v73
	v_cvt_pk_bf16_f32 v69, v74, v75
	v_cvt_pk_bf16_f32 v83, v70, v71
	s_waitcnt vmcnt(12)
	v_cvt_pk_bf16_f32 v70, v76, v77
	v_and_b32_e32 v56, 0xffff0000, v80
	v_and_b32_e32 v58, 0xffff0000, v81
	v_and_b32_e32 v75, 0xffff0000, v68
	v_and_b32_e32 v77, 0xffff0000, v69
	v_cvt_pk_bf16_f32 v71, v78, v79
	v_lshlrev_b32_e32 v0, 16, v80
	v_lshlrev_b32_e32 v57, 16, v81
	v_and_b32_e32 v67, 0xffff0000, v82
	v_lshlrev_b32_e32 v74, 16, v68
	v_lshlrev_b32_e32 v76, 16, v69
	v_and_b32_e32 v79, 0xffff0000, v70
	v_mul_f32_e32 v56, v56, v56
	v_mul_f32_e32 v58, v58, v58
	v_mul_f32_e32 v75, v75, v75
	v_mul_f32_e32 v77, v77, v77
	v_lshlrev_b32_e32 v59, 16, v82
	v_and_b32_e32 v73, 0xffff0000, v83
	v_lshlrev_b32_e32 v78, 16, v70
	v_and_b32_e32 v85, 0xffff0000, v71
	v_mul_f32_e32 v67, v67, v67
	v_mul_f32_e32 v79, v79, v79
	v_fmac_f32_e32 v56, v0, v0
	v_fmac_f32_e32 v58, v57, v57
	v_fmac_f32_e32 v75, v74, v74
	v_fmac_f32_e32 v77, v76, v76
	v_lshlrev_b32_e32 v72, 16, v83
	v_lshlrev_b32_e32 v84, 16, v71
	v_mul_f32_e32 v73, v73, v73
	v_mul_f32_e32 v85, v85, v85
	v_fmac_f32_e32 v67, v59, v59
	v_fmac_f32_e32 v79, v78, v78
	v_add_f32_e32 v0, v56, v58
	v_add_f32_e32 v56, v75, v77
	v_fmac_f32_e32 v73, v72, v72
	v_fmac_f32_e32 v85, v84, v84
	v_add_f32_e32 v0, v0, v67
	v_add_f32_e32 v56, v56, v79
	v_add_f32_e32 v0, v73, v0
	v_add_f32_e32 v56, v85, v56
	v_add_f32_e32 v0, v0, v56
	ds_bpermute_b32 v56, v61, v0
	v_lshl_add_u64 v[58:59], s[8:9], 0, v[50:51]
	s_waitcnt lgkmcnt(0)
	v_add_f32_e32 v0, v0, v56
	ds_bpermute_b32 v56, v62, v0
	s_waitcnt lgkmcnt(0)
	v_add_f32_e32 v0, v0, v56
	ds_bpermute_b32 v56, v63, v0
	s_waitcnt lgkmcnt(0)
	v_add_f32_e32 v0, v0, v56
	ds_bpermute_b32 v56, v64, v0
	s_waitcnt lgkmcnt(0)
	v_add_f32_e32 v0, v0, v56
	ds_bpermute_b32 v56, v65, v0
	s_waitcnt lgkmcnt(0)
	v_add_f32_e32 v0, v0, v56
	ds_bpermute_b32 v67, v66, v0
	v_add_co_u32_e32 v56, vcc, s4, v58
	s_nop 1
	v_addc_co_u32_e32 v57, vcc, 0, v59, vcc
	global_store_dwordx4 v[56:57], v[80:83], off nt
	global_store_dwordx4 v[56:57], v[68:71], off offset:1024 nt
	v_lshl_add_u64 v[56:57], s[8:9], 0, v[54:55]
	s_and_saveexec_b64 s[22:23], s[40:41]
	s_cbranch_execz .LBB0_33
	s_waitcnt lgkmcnt(0)
	v_add_f32_e32 v0, v0, v67
	v_add_co_u32_e32 v68, vcc, 0x17100000, v56
	v_cndmask_b32_e64 v0, 0, v0, s[42:43]
	s_nop 0
	v_addc_co_u32_e32 v69, vcc, 0, v57, vcc
	global_store_dword v[68:69], v0, off
.LBB0_33:
	s_or_b64 exec, exec, s[22:23]
	s_waitcnt vmcnt(9)
	v_cvt_pk_bf16_f32 v46, v46, v47
	s_waitcnt vmcnt(7)
	v_cvt_pk_bf16_f32 v38, v38, v39
	v_cvt_pk_bf16_f32 v47, v48, v49
	v_cvt_pk_bf16_f32 v48, v42, v43
	v_and_b32_e32 v42, 0xffff0000, v46
	v_cvt_pk_bf16_f32 v39, v40, v41
	s_waitcnt vmcnt(6)
	v_cvt_pk_bf16_f32 v40, v34, v35
	v_and_b32_e32 v35, 0xffff0000, v38
	v_lshlrev_b32_e32 v0, 16, v46
	v_mul_f32_e32 v42, v42, v42
	v_and_b32_e32 v43, 0xffff0000, v47
	v_cvt_pk_bf16_f32 v41, v36, v37
	v_lshlrev_b32_e32 v34, 16, v38
	v_mul_f32_e32 v35, v35, v35
	v_and_b32_e32 v36, 0xffff0000, v39
	v_fmac_f32_e32 v42, v0, v0
	v_lshlrev_b32_e32 v0, 16, v47
	v_mul_f32_e32 v43, v43, v43
	v_fmac_f32_e32 v35, v34, v34
	v_lshlrev_b32_e32 v34, 16, v39
	v_mul_f32_e32 v36, v36, v36
	v_fmac_f32_e32 v43, v0, v0
	v_fmac_f32_e32 v36, v34, v34
	v_add_f32_e32 v0, v42, v43
	v_and_b32_e32 v43, 0xffff0000, v48
	v_add_f32_e32 v34, v35, v36
	v_and_b32_e32 v36, 0xffff0000, v40
	v_lshlrev_b32_e32 v42, 16, v48
	v_mul_f32_e32 v43, v43, v43
	v_lshlrev_b32_e32 v35, 16, v40
	v_mul_f32_e32 v36, v36, v36
	v_cvt_pk_bf16_f32 v49, v44, v45
	v_fmac_f32_e32 v43, v42, v42
	v_fmac_f32_e32 v36, v35, v35
	v_add_f32_e32 v0, v0, v43
	v_and_b32_e32 v43, 0xffff0000, v49
	v_add_f32_e32 v34, v34, v36
	v_and_b32_e32 v36, 0xffff0000, v41
	v_lshlrev_b32_e32 v42, 16, v49
	v_mul_f32_e32 v43, v43, v43
	v_lshlrev_b32_e32 v35, 16, v41
	v_mul_f32_e32 v36, v36, v36
	v_fmac_f32_e32 v43, v42, v42
	v_fmac_f32_e32 v36, v35, v35
	v_add_f32_e32 v0, v43, v0
	v_add_f32_e32 v34, v36, v34
	v_add_f32_e32 v0, v0, v34
	ds_bpermute_b32 v34, v61, v0
	v_add_co_u32_e32 v36, vcc, 0x3100000, v58
	s_waitcnt lgkmcnt(0)
	v_add_f32_e32 v0, v0, v34
	ds_bpermute_b32 v34, v62, v0
	v_addc_co_u32_e32 v37, vcc, 0, v59, vcc
	global_store_dwordx4 v[36:37], v[46:49], off offset:2048 nt
	global_store_dwordx4 v[36:37], v[38:41], off offset:3072 nt
	s_waitcnt lgkmcnt(0)
	v_add_f32_e32 v0, v0, v34
	ds_bpermute_b32 v34, v63, v0
	s_waitcnt lgkmcnt(0)
	v_add_f32_e32 v0, v0, v34
	ds_bpermute_b32 v34, v64, v0
	s_waitcnt lgkmcnt(0)
	v_add_f32_e32 v0, v0, v34
	ds_bpermute_b32 v34, v65, v0
	s_waitcnt lgkmcnt(0)
	v_add_f32_e32 v0, v0, v34
	ds_bpermute_b32 v34, v66, v0
	s_and_saveexec_b64 s[22:23], s[40:41]
	s_cbranch_execz .LBB0_35
	s_waitcnt lgkmcnt(0)
	v_add_f32_e32 v0, v0, v34
	v_add_co_u32_e32 v34, vcc, 0x17100000, v56
	v_cndmask_b32_e64 v0, 0, v0, s[42:43]
	s_nop 0
	v_addc_co_u32_e32 v35, vcc, 0, v57, vcc
	global_store_dword v[34:35], v0, off offset:4
.LBB0_35:
	s_or_b64 exec, exec, s[22:23]
	s_waitcnt vmcnt(7)
	v_cvt_pk_bf16_f32 v26, v26, v27
	v_cvt_pk_bf16_f32 v27, v28, v29
	s_waitcnt vmcnt(6)
	v_cvt_pk_bf16_f32 v28, v22, v23
	v_and_b32_e32 v22, 0xffff0000, v26
	v_lshlrev_b32_e32 v0, 16, v26
	v_mul_f32_e32 v22, v22, v22
	v_and_b32_e32 v23, 0xffff0000, v27
	v_fmac_f32_e32 v22, v0, v0
	v_lshlrev_b32_e32 v0, 16, v27
	v_mul_f32_e32 v23, v23, v23
	v_fmac_f32_e32 v23, v0, v0
	v_add_f32_e32 v0, v22, v23
	v_and_b32_e32 v23, 0xffff0000, v28
	v_lshlrev_b32_e32 v22, 16, v28
	v_mul_f32_e32 v23, v23, v23
	v_cvt_pk_bf16_f32 v29, v24, v25
	v_fmac_f32_e32 v23, v22, v22
	v_add_f32_e32 v0, v0, v23
	v_and_b32_e32 v23, 0xffff0000, v29
	v_lshlrev_b32_e32 v22, 16, v29
	v_mul_f32_e32 v23, v23, v23
	v_fmac_f32_e32 v23, v22, v22
	s_waitcnt vmcnt(5)
	v_cvt_pk_bf16_f32 v22, v18, v19
	v_add_f32_e32 v0, v23, v0
	v_cvt_pk_bf16_f32 v23, v20, v21
	v_and_b32_e32 v19, 0xffff0000, v22
	v_lshlrev_b32_e32 v18, 16, v22
	v_mul_f32_e32 v19, v19, v19
	v_and_b32_e32 v20, 0xffff0000, v23
	v_fmac_f32_e32 v19, v18, v18
	v_lshlrev_b32_e32 v18, 16, v23
	v_mul_f32_e32 v20, v20, v20
	s_waitcnt vmcnt(4)
	v_cvt_pk_bf16_f32 v24, v30, v31
	v_fmac_f32_e32 v20, v18, v18
	v_add_f32_e32 v18, v19, v20
	v_and_b32_e32 v20, 0xffff0000, v24
	v_lshlrev_b32_e32 v19, 16, v24
	v_mul_f32_e32 v20, v20, v20
	v_cvt_pk_bf16_f32 v25, v32, v33
	v_fmac_f32_e32 v20, v19, v19
	v_add_f32_e32 v18, v18, v20
	v_and_b32_e32 v20, 0xffff0000, v25
	v_lshlrev_b32_e32 v19, 16, v25
	v_mul_f32_e32 v20, v20, v20
	v_fmac_f32_e32 v20, v19, v19
	v_add_f32_e32 v18, v20, v18
	v_add_f32_e32 v0, v0, v18
	ds_bpermute_b32 v18, v61, v0
	v_add_co_u32_e32 v20, vcc, 0x3101000, v58
	s_waitcnt lgkmcnt(0)
	v_add_f32_e32 v0, v0, v18
	ds_bpermute_b32 v18, v62, v0
	v_addc_co_u32_e32 v21, vcc, 0, v59, vcc
	global_store_dwordx4 v[20:21], v[26:29], off nt
	global_store_dwordx4 v[20:21], v[22:25], off offset:1024 nt
	s_waitcnt lgkmcnt(0)
	v_add_f32_e32 v0, v0, v18
	ds_bpermute_b32 v18, v63, v0
	s_waitcnt lgkmcnt(0)
	v_add_f32_e32 v0, v0, v18
	ds_bpermute_b32 v18, v64, v0
	s_waitcnt lgkmcnt(0)
	v_add_f32_e32 v0, v0, v18
	ds_bpermute_b32 v18, v65, v0
	s_waitcnt lgkmcnt(0)
	v_add_f32_e32 v0, v0, v18
	ds_bpermute_b32 v18, v66, v0
	s_and_saveexec_b64 s[22:23], s[40:41]
	s_cbranch_execz .LBB0_37
	s_waitcnt lgkmcnt(0)
	v_add_f32_e32 v0, v0, v18
	v_add_co_u32_e32 v18, vcc, 0x17100000, v56
	v_cndmask_b32_e64 v0, 0, v0, s[42:43]
	s_nop 0
	v_addc_co_u32_e32 v19, vcc, 0, v57, vcc
	global_store_dword v[18:19], v0, off offset:8
.LBB0_37:
	s_or_b64 exec, exec, s[22:23]
	v_cvt_pk_bf16_f32 v14, v14, v15
	v_cvt_pk_bf16_f32 v6, v6, v7
	v_cvt_pk_bf16_f32 v15, v16, v17
	v_cvt_pk_bf16_f32 v16, v10, v11
	v_and_b32_e32 v10, 0xffff0000, v14
	v_cvt_pk_bf16_f32 v7, v8, v9
	v_cvt_pk_bf16_f32 v8, v2, v3
	v_and_b32_e32 v3, 0xffff0000, v6
	v_lshlrev_b32_e32 v0, 16, v14
	v_mul_f32_e32 v10, v10, v10
	v_and_b32_e32 v11, 0xffff0000, v15
	v_cvt_pk_bf16_f32 v9, v4, v5
	v_lshlrev_b32_e32 v2, 16, v6
	v_mul_f32_e32 v3, v3, v3
	v_and_b32_e32 v4, 0xffff0000, v7
	v_fmac_f32_e32 v10, v0, v0
	v_lshlrev_b32_e32 v0, 16, v15
	v_mul_f32_e32 v11, v11, v11
	v_fmac_f32_e32 v3, v2, v2
	v_lshlrev_b32_e32 v2, 16, v7
	v_mul_f32_e32 v4, v4, v4
	v_fmac_f32_e32 v11, v0, v0
	v_fmac_f32_e32 v4, v2, v2
	v_add_f32_e32 v0, v10, v11
	v_and_b32_e32 v11, 0xffff0000, v16
	v_add_f32_e32 v2, v3, v4
	v_and_b32_e32 v4, 0xffff0000, v8
	v_lshlrev_b32_e32 v10, 16, v16
	v_mul_f32_e32 v11, v11, v11
	v_lshlrev_b32_e32 v3, 16, v8
	v_mul_f32_e32 v4, v4, v4
	v_cvt_pk_bf16_f32 v17, v12, v13
	v_fmac_f32_e32 v11, v10, v10
	v_fmac_f32_e32 v4, v3, v3
	v_add_f32_e32 v0, v0, v11
	v_and_b32_e32 v11, 0xffff0000, v17
	v_add_f32_e32 v2, v2, v4
	v_and_b32_e32 v4, 0xffff0000, v9
	v_lshlrev_b32_e32 v10, 16, v17
	v_mul_f32_e32 v11, v11, v11
	v_lshlrev_b32_e32 v3, 16, v9
	v_mul_f32_e32 v4, v4, v4
	v_fmac_f32_e32 v11, v10, v10
	v_fmac_f32_e32 v4, v3, v3
	v_add_f32_e32 v0, v11, v0
	v_add_f32_e32 v2, v4, v2
	v_add_f32_e32 v0, v0, v2
	ds_bpermute_b32 v2, v61, v0
	v_add_co_u32_e32 v4, vcc, 0x3101000, v58
	s_waitcnt lgkmcnt(0)
	v_add_f32_e32 v0, v0, v2
	ds_bpermute_b32 v2, v62, v0
	v_addc_co_u32_e32 v5, vcc, 0, v59, vcc
	global_store_dwordx4 v[4:5], v[14:17], off offset:2048 nt
	global_store_dwordx4 v[4:5], v[6:9], off offset:3072 nt
	s_waitcnt lgkmcnt(0)
	v_add_f32_e32 v0, v0, v2
	ds_bpermute_b32 v2, v63, v0
	s_waitcnt lgkmcnt(0)
	v_add_f32_e32 v0, v0, v2
	ds_bpermute_b32 v2, v64, v0
	s_waitcnt lgkmcnt(0)
	v_add_f32_e32 v0, v0, v2
	ds_bpermute_b32 v2, v65, v0
	s_waitcnt lgkmcnt(0)
	v_add_f32_e32 v0, v0, v2
	ds_bpermute_b32 v2, v66, v0
	s_and_saveexec_b64 s[22:23], s[40:41]
	s_cbranch_execz .LBB0_30
	s_waitcnt lgkmcnt(0)
	v_add_f32_e32 v0, v0, v2
	v_add_co_u32_e32 v2, vcc, 0x17100000, v56
	v_cndmask_b32_e64 v0, 0, v0, s[42:43]
	s_nop 0
	v_addc_co_u32_e32 v3, vcc, 0, v57, vcc
	global_store_dword v[2:3], v0, off offset:12
	s_branch .LBB0_30
